# v31 plus: grid barrier between phase 0 and phase 1 replaced by a release/acquire counter hand-off on the adaLN mod table
# baseline (speedup 1.0000x reference)
; #define SUB(id, ...) do { __VA_ARGS__; if (SUBP == (id)) { __syncthreads(); __VA_ARGS__; } } while (0)
; #define LAS __attribute__((address_space(3)))
; DI void phase0(const Params& p, LAS unsigned char* lds) {
;     ...
;     SUB(0, for (int u = blockIdx.x; u < 192; u += G) p0_mod_unit(p, u, lds));
;     LAS float* scr = (LAS float*)(lds + wid * 16384);
;     const int gw = blockIdx.x * NWAVES + wid, NGW = G * NWAVES;
;     constexpr int I_INE = 16 * 256, I_OUTE = 32 * 32, I_INO = 16 * 192, I_OUTO = 32 * 32, I_PW = 4 * 32;
;     constexpr int NITEMS = I_INE + I_OUTE + I_INO + I_OUTO + I_PW;
;     for (int it = (NGW - 1 - gw); it < NITEMS; it += NGW) {
.LBB0_32:
	s_cmpk_gt_i32 s2, 0xbf
	s_cbranch_scc1 .Lmodpub_done
	s_waitcnt vmcnt(0)
	s_barrier
	v_cmp_eq_u32_e32 vcc, 0, v226
	s_and_saveexec_b64 s[4:5], vcc
	s_cbranch_execz .Lmodpub_skip
	buffer_wbl2 sc1
	s_waitcnt vmcnt(0)
	v_mov_b32_e32 v0, 0x3cf0
	v_mov_b32_e32 v1, 1
	global_atomic_add v0, v1, s[28:29]
.Lmodpub_skip:
	s_or_b64 exec, exec, s[4:5]
.Lmodpub_done:
	v_ashrrev_i32_e32 v0, 6, v166
	s_lshl_b32 s0, s2, 3
	v_add_u32_e32 v1, s0, v0
	s_lshl_b32 s90, s22, 3
	v_writelane_b32 v251, s0, 3
	v_xad_u32 v26, v1, -1, s90
	s_movk_i32 s0, 0x2480
	v_cmp_gt_i32_e32 vcc, s0, v26
	s_and_saveexec_b64 s[0:1], vcc
	s_cbranch_execz .LBB0_51
	v_bfe_u32 v27, v166, 5, 1
	v_and_b32_e32 v18, 31, v166
	v_lshl_add_u32 v3, v0, 14, 0
	v_lshlrev_b32_e32 v0, 2, v18
	v_mul_u32_u24_e32 v4, 0x84, v27
	v_add3_u32 v28, v3, v0, v4
	v_lshlrev_b32_e32 v4, 3, v166
	v_bfe_u32 v29, v166, 3, 3
	v_and_b32_e32 v20, 56, v4
	v_and_b32_e32 v2, 63, v166
	v_mov_b32_e32 v1, 0
	v_mul_u32_u24_e32 v4, 0x84, v20
	v_lshlrev_b32_e32 v5, 2, v29
	v_add3_u32 v30, v3, v4, v5
	v_bfe_u32 v34, v2, 3, 2
	s_waitcnt lgkmcnt(0)
	v_lshl_add_u64 v[2:3], s[48:49], 0, v[0:1]
	v_lshl_add_u64 v[4:5], s[42:43], 0, v[0:1]
	v_lshl_add_u64 v[6:7], s[66:67], 0, v[0:1]
	v_lshl_add_u64 v[8:9], s[60:61], 0, v[0:1]
	v_lshlrev_b32_e32 v0, 1, v20
	v_lshl_add_u64 v[16:17], s[26:27], 0, v[0:1]
	s_mov_b64 s[6:7], 0x2200000
	v_lshl_add_u64 v[10:11], v[16:17], 0, s[6:7]
	s_mov_b64 s[6:7], 0x1600000
	v_lshl_add_u64 v[12:13], v[16:17], 0, s[6:7]
	s_mov_b64 s[6:7], 0x1200000
	s_add_u32 s4, s26, 0x2600000
	v_lshl_add_u64 v[14:15], v[16:17], 0, s[6:7]
	s_mov_b64 s[6:7], 0x200000
	v_lshlrev_b32_e32 v0, 1, v29
	v_or_b32_e32 v31, 8, v29
	v_or_b32_e32 v32, 16, v29
	v_or_b32_e32 v33, 24, v29
	s_addc_u32 s5, s27, 0
	v_lshl_add_u64 v[16:17], v[16:17], 0, s[6:7]
	v_lshlrev_b32_e32 v35, 5, v26
	s_lshl_b32 s3, s90, 5
	v_lshl_or_b32 v36, v26, 6, v0
	s_lshl_b32 s16, s90, 6
	v_lshlrev_b32_e32 v37, 7, v26
	s_lshl_b32 s17, s90, 7
	v_lshlrev_b32_e32 v38, 1, v26
	s_lshl_b32 s18, s90, 1
	v_lshlrev_b32_e32 v39, 3, v26
	s_lshl_b32 s19, s90, 3
	v_lshlrev_b32_e32 v18, 2, v18
	s_movk_i32 s30, 0x1000
	s_mov_b32 s31, 0xc000
	v_lshlrev_b32_e32 v20, 1, v20
	s_mov_b32 s34, 0x1c000
	s_mov_b32 s35, 0x48000
	s_mov_b32 s38, 0x54000
	s_mov_b32 s39, 0x60000
	s_mov_b32 s40, 0x6c000
	s_mov_b32 s41, 0x78000
	s_mov_b32 s42, 0x84000
	s_mov_b32 s43, 0x90000
	s_mov_b32 s48, 0x9c000
	v_add_u32_e32 v40, 0x400, v28
	v_add_u32_e32 v41, 0x800, v28
	v_add_u32_e32 v42, 0xc00, v28
	v_add_u32_e32 v43, 0x1000, v28
	v_add_u32_e32 v44, 0x1400, v28
	v_add_u32_e32 v45, 0x1800, v28
	v_add_u32_e32 v46, 0x1c00, v28
	s_mov_b32 s49, 0xa8000
	s_mov_b32 s56, 0xb4000
	s_mov_b32 s57, 0xc0000
	s_mov_b32 s58, 0xcc000
	s_mov_b32 s59, 0xd8000
	s_mov_b32 s60, 0xe4000
	s_mov_b32 s61, 0xf0000
	s_mov_b32 s66, 0xfc000
	s_mov_b32 s67, 0x108000
	s_mov_b32 s72, 0x114000
	s_mov_b32 s73, 0x120000
	s_mov_b32 s74, 0x12c000
	s_mov_b32 s75, 0x138000
	s_mov_b32 s84, 0x144000
	s_mov_b32 s85, 0x150000
	s_mov_b32 s86, 0x15c000
	s_mov_b32 s87, 0x168000
	s_mov_b32 s88, 0x174000
	s_movk_i32 s89, 0x48
	s_movk_i32 s92, 0x58
	s_movk_i32 s93, 0x68
	s_movk_i32 s94, 0x78
	s_movk_i32 s95, 0x247f
	s_mov_b64 s[6:7], 0
	s_branch .LBB0_35

; DI unsigned xb_ld(unsigned* p)              { return __hip_atomic_load(p, __ATOMIC_RELAXED, __HIP_MEMORY_SCOPE_AGENT); }
; DI unsigned xb_add(unsigned* p, unsigned v) { return __hip_atomic_fetch_add(p, v, __ATOMIC_RELAXED, __HIP_MEMORY_SCOPE_AGENT); }
; #define XB_SPIN(cond, bar) do { unsigned _sp = 0; while (cond) { __builtin_amdgcn_s_sleep(1); \
;     if ((++_sp & 255u) == 0u) { if (xb_ld(&(bar)[XB_TMO])) break; if (_sp > XB_SPIN_CAP) { atomicAdd(&(bar)[XB_TMO], 1u); break; } } } } while (0)
; DI void xcd_barrier(const XcdBarrier& b) {
;     asm volatile("s_waitcnt vmcnt(0)" ::: "memory");
;     __syncthreads();
;     if (threadIdx.x == 0) {
;         unsigned* bar = b.bar;
;         __builtin_amdgcn_s_waitcnt(0);
;         unsigned nloc = b.st[0], nx = b.st[1];
;         if (nloc == 0u) { xcd_barrier_complete(bar, b.x, nloc, nx); b.st[0] = nloc; b.st[1] = nx; }
;         const unsigned old = xb_add(&bar[XB_XSUB(b.x)], 1u);
;         const unsigned gen = old / nloc;
;         if (old + 1u == (gen + 1u) * nloc) {
;             __builtin_amdgcn_fence(__ATOMIC_RELEASE, "agent");
;             asm volatile("s_waitcnt vmcnt(0)" ::: "memory");
;             const unsigned og = xb_add(&bar[XB_TOP], 1u);
;             const unsigned tg = og / nx;
;             if (og + 1u == (tg + 1u) * nx) xb_add(&bar[XB_TOPGEN], 1u);
;             else XB_SPIN(xb_ld(&bar[XB_TOPGEN]) == tg, bar);
;             __builtin_amdgcn_fence(__ATOMIC_ACQUIRE, "agent");
;             xb_add(&bar[XB_XGEN(b.x)], 1u);
;             asm volatile("s_waitcnt vmcnt(0)" ::: "memory");
;         } else {
;             XB_SPIN(xb_ld(&bar[XB_XGEN(b.x)]) == gen, bar);
;             __builtin_amdgcn_fence(__ATOMIC_ACQUIRE, "agent");
;             asm volatile("s_waitcnt vmcnt(0)" ::: "memory");
;         }
;     }
;     __syncthreads();
; }
.LBB0_51:
	s_or_b64 exec, exec, s[0:1]
	s_waitcnt vmcnt(0)
	s_waitcnt lgkmcnt(0)
	s_barrier
	s_and_saveexec_b64 s[0:1], s[20:21]
	s_cbranch_execz .LBB0_103
	v_mov_b32_e32 v0, 0x3cf0
	s_mov_b32 s3, 0
.Lmodwait:
	global_load_dword v1, v0, s[28:29] sc1
	s_waitcnt vmcnt(0)
	v_readfirstlane_b32 s4, v1
	s_nop 3
	s_cmp_ge_u32 s4, 0xc0
	s_cbranch_scc1 .Lmodwait_done
	s_sleep 1
	s_add_i32 s3, s3, 1
	s_cmp_lt_u32 s3, 0x400000
	s_cbranch_scc1 .Lmodwait
.Lmodwait_done:
	buffer_inv sc1
	s_waitcnt vmcnt(0)
